# adds: up-proj fused epilogue reuses one hoisted set of second-group conv-weight loads (no store drains); LRU unit loops drop stale weight vmcnt waits
# speedup vs baseline: 1.0190x; 1.0023x over previous
;     __device__ __forceinline__ void operator()(const f32x4 (&acc)[2][2][4][2], const Unit& u, int wr, int wc, int fr, int fq) const {
;         const int row0 = u.pm * BM + wr * 64 + fr, ch0 = u.pn * HALF + wc * 32 + 8 * fq;
; #pragma unroll
;         for (int ai = 0; ai < 2; ++ai) {
;             float rs[4];
; #pragma unroll
;             for (int m = 0; m < 4; ++m) rs[m] = __builtin_amdgcn_rsqf(SS[grow0 + row0 + ai * HALF + m * 16] * (1.0f / 1024.0f) + 1e-6f);
;             const int er = ((u.pm * 4 + 2 * ai + wr) * 2) * 9216;
; #pragma unroll
;             for (int n = 0; n < 2; ++n) {
;                 const int ch = ch0 + 4 * n;
;                 const f32x4 w0 = *(const f32x4*)(cw + ch), w1 = *(const f32x4*)(cw + 3072 + ch), w2 = *(const f32x4*)(cw + 6144 + ch), bb = *(const f32x4*)(cb + ch);
;                 float o[4][4], pp[4][4], gg[4][4];
; #pragma unroll
;                 for (int e = 0; e < 4; ++e) {
;                     float g[4], R[4], L[4];
; #pragma unroll
;                     for (int m = 0; m < 4; ++m) { g[m] = acc[ai][0][m][n][e] * rs[m];
;                         R[m] = __builtin_bit_cast(float, __builtin_amdgcn_mov_dpp(__builtin_bit_cast(int, g[m]), 0x121, 0xf, 0xf, true)); L[m] = __builtin_bit_cast(float, __builtin_amdgcn_mov_dpp(__builtin_bit_cast(int, g[m]), 0x12F, 0xf, 0xf, true)); }
; #pragma unroll
;                     for (int m = 0; m < 4; ++m) {
;                         const float gp = (fr == 0) ? (m > 0 ? R[m > 0 ? m - 1 : 0] : 0.f) : R[m];
;                         const float gn = (fr == 15) ? (m < 3 ? L[m < 3 ? m + 1 : 3] : 0.f) : L[m];
;                         const float pre = bb[e] + w0[e] * gp + w1[e] * g[m] + w2[e] * gn;
;                         pp[m][e] = pre; gg[m][e] = g[m];
.LBB0_859:
	v_lshl_add_u32 v181, s72, 8, v176
	v_add_u32_e32 v134, s42, v181
	v_ashrrev_i32_e32 v135, 31, v134
	v_lshl_add_u64 v[134:135], v[134:135], 2, s[24:25]
	global_load_dword v172, v[134:135], off
	global_load_dword v173, v[134:135], off offset:64
	global_load_dword v174, v[134:135], off offset:128
	global_load_dword v175, v[134:135], off offset:192
	v_lshl_or_b32 v162, s74, 7, v178
	v_ashrrev_i32_e32 v163, 31, v162
	v_lshlrev_b64 v[142:143], 2, v[162:163]
	v_lshl_add_u64 v[164:165], s[16:17], 0, v[142:143]
	v_lshl_add_u64 v[166:167], s[18:19], 0, v[142:143]
	global_load_dwordx4 v[146:149], v[164:165], off
	global_load_dwordx4 v[134:137], v[166:167], off
	v_lshl_add_u64 v[168:169], s[60:61], 0, v[142:143]
	global_load_dwordx4 v[138:141], v[168:169], off
	v_lshl_add_u64 v[170:171], s[62:63], 0, v[142:143]
	global_load_dwordx4 v[142:145], v[170:171], off
	global_load_dwordx4 v[232:235], v[164:165], off offset:16
	global_load_dwordx4 v[236:239], v[166:167], off offset:16
	global_load_dwordx4 v[240:243], v[168:169], off offset:16
	global_load_dwordx4 v[244:247], v[170:171], off offset:16
	s_waitcnt vmcnt(0)
	v_fmamk_f32 v172, v172, 0x3a800000, v188
	v_rsq_f32_e32 v172, v172
	v_fmamk_f32 v173, v173, 0x3a800000, v188
	v_fmamk_f32 v174, v174, 0x3a800000, v188
	v_fmamk_f32 v175, v175, 0x3a800000, v188
	v_rsq_f32_e32 v183, v173
	v_rsq_f32_e32 v182, v174
	v_rsq_f32_e32 v174, v175
	v_pk_mul_f32 v[130:131], v[130:131], v[172:173] op_sel_hi:[1,0]
	v_pk_mul_f32 v[132:133], v[132:133], v[172:173] op_sel_hi:[1,0]
	v_mul_f32_e32 v220, v126, v183
	v_mov_b32_dpp v227, v130 row_ror:1 row_mask:0xf bank_mask:0xf bound_ctrl:1
	v_mov_b32_dpp v224, v131 row_ror:1 row_mask:0xf bank_mask:0xf bound_ctrl:1
	v_mov_b32_dpp v211, v132 row_ror:1 row_mask:0xf bank_mask:0xf bound_ctrl:1
	v_mov_b32_dpp v207, v133 row_ror:1 row_mask:0xf bank_mask:0xf bound_ctrl:1
	v_mul_f32_e32 v208, v122, v182
	v_mul_f32_e32 v217, v127, v183
	v_mul_f32_e32 v206, v123, v182
	v_mul_f32_e32 v205, v128, v183
	v_mul_f32_e32 v202, v129, v183
	v_cndmask_b32_e64 v123, v224, 0, s[4:5]
	v_cndmask_b32_e64 v122, v227, 0, s[4:5]
	v_cndmask_b32_e64 v229, v207, 0, s[4:5]
	v_cndmask_b32_e64 v228, v211, 0, s[4:5]
	v_pk_mul_f32 v[118:119], v[118:119], v[174:175] op_sel_hi:[1,0]
	v_mul_f32_e32 v127, v124, v182
	v_mul_f32_e32 v126, v125, v182
	v_pk_mul_f32 v[120:121], v[120:121], v[174:175] op_sel_hi:[1,0]
	v_mov_b32_dpp v226, v220 row_ror:15 row_mask:0xf bank_mask:0xf bound_ctrl:1
	v_mov_b32_dpp v124, v130 row_ror:15 row_mask:0xf bank_mask:0xf bound_ctrl:1
	v_mov_b32_dpp v125, v131 row_ror:15 row_mask:0xf bank_mask:0xf bound_ctrl:1
	v_mov_b32_dpp v225, v217 row_ror:15 row_mask:0xf bank_mask:0xf bound_ctrl:1
	v_mov_b32_dpp v210, v205 row_ror:15 row_mask:0xf bank_mask:0xf bound_ctrl:1
	v_mov_b32_dpp v173, v132 row_ror:15 row_mask:0xf bank_mask:0xf bound_ctrl:1
	v_mov_b32_dpp v175, v133 row_ror:15 row_mask:0xf bank_mask:0xf bound_ctrl:1
	v_mov_b32_dpp v209, v202 row_ror:15 row_mask:0xf bank_mask:0xf bound_ctrl:1
	v_pk_fma_f32 v[122:123], v[146:147], v[122:123], v[134:135]
	v_pk_fma_f32 v[228:229], v[148:149], v[228:229], v[136:137]
	v_cndmask_b32_e64 v125, v125, v225, s[8:9]
	v_cndmask_b32_e64 v124, v124, v226, s[8:9]
	v_cndmask_b32_e64 v231, v175, v209, s[8:9]
	v_cndmask_b32_e64 v230, v173, v210, s[8:9]
	v_pk_fma_f32 v[122:123], v[130:131], v[138:139], v[122:123]
	v_pk_fma_f32 v[228:229], v[132:133], v[140:141], v[228:229]
	v_mov_b32_dpp v223, v220 row_ror:1 row_mask:0xf bank_mask:0xf bound_ctrl:1
	v_mov_b32_dpp v219, v208 row_ror:1 row_mask:0xf bank_mask:0xf bound_ctrl:1
	v_mov_b32_dpp v222, v208 row_ror:15 row_mask:0xf bank_mask:0xf bound_ctrl:1
	v_mov_b32_dpp v216, v217 row_ror:1 row_mask:0xf bank_mask:0xf bound_ctrl:1
	v_mov_b32_dpp v212, v206 row_ror:1 row_mask:0xf bank_mask:0xf bound_ctrl:1
	v_mov_b32_dpp v218, v206 row_ror:15 row_mask:0xf bank_mask:0xf bound_ctrl:1
	v_mov_b32_dpp v221, v118 row_ror:1 row_mask:0xf bank_mask:0xf bound_ctrl:1
	v_mov_b32_dpp v213, v118 row_ror:15 row_mask:0xf bank_mask:0xf bound_ctrl:1
	v_mov_b32_dpp v215, v119 row_ror:1 row_mask:0xf bank_mask:0xf bound_ctrl:1
	v_mov_b32_dpp v214, v119 row_ror:15 row_mask:0xf bank_mask:0xf bound_ctrl:1
	v_mov_b32_dpp v204, v205 row_ror:1 row_mask:0xf bank_mask:0xf bound_ctrl:1
	v_mov_b32_dpp v187, v127 row_ror:1 row_mask:0xf bank_mask:0xf bound_ctrl:1
	v_mov_b32_dpp v203, v127 row_ror:15 row_mask:0xf bank_mask:0xf bound_ctrl:1
	v_mov_b32_dpp v184, v202 row_ror:1 row_mask:0xf bank_mask:0xf bound_ctrl:1
	v_mov_b32_dpp v185, v126 row_ror:1 row_mask:0xf bank_mask:0xf bound_ctrl:1
	v_mov_b32_dpp v186, v126 row_ror:15 row_mask:0xf bank_mask:0xf bound_ctrl:1
	v_mov_b32_dpp v200, v120 row_ror:1 row_mask:0xf bank_mask:0xf bound_ctrl:1
	v_mov_b32_dpp v129, v120 row_ror:15 row_mask:0xf bank_mask:0xf bound_ctrl:1
	v_mov_b32_dpp v201, v121 row_ror:1 row_mask:0xf bank_mask:0xf bound_ctrl:1
	v_mov_b32_dpp v128, v121 row_ror:15 row_mask:0xf bank_mask:0xf bound_ctrl:1
	v_pk_fma_f32 v[122:123], v[142:143], v[124:125], v[122:123]
	v_pk_fma_f32 v[124:125], v[144:145], v[230:231], v[228:229]
	s_and_saveexec_b64 s[74:75], s[6:7]
	s_movk_i32 s67, 0x1800
	s_cbranch_execz .LBB0_861
; __device__ __forceinline__ unsigned cvt_pk_bf16(float lo, float hi) { unsigned r; asm volatile("v_cvt_pk_bf16_f32 %0, %1, %2" : "=v"(r) : "v"(lo), "v"(hi)); return r; }
; __device__ __forceinline__ float gelu_tanh_f(float x) { const float u = 0.7978845608028654f * (x + 0.044715f * x * x * x); return x * fast_rcp(1.0f + __expf(-2.0f * u)); }
;     __device__ __forceinline__ void operator()(const f32x4 (&acc)[2][2][4][2], const Unit& u, int wr, int wc, int fr, int fq) const {
;     ...
;                         const float pre = bb[e] + w0[e] * gp + w1[e] * g[m] + w2[e] * gn;
;                         pp[m][e] = pre; gg[m][e] = g[m];
;                         o[m][e] = gelu_tanh_f(pre) * (acc[ai][1][m][n][e] * rs[m]);
;                     }
;                 }
; #pragma unroll
;                 for (int m = 0; m < 4; ++m) {
;                     const bool edge = (m == 0 && fr == 0) || (m == 3 && fr == 15);
;                     if (!edge) { u32x2 w; w.x = cvt_pk_bf16(o[m][0], o[m][1]); w.y = cvt_pk_bf16(o[m][2], o[m][3]); *(u32x2*)(H + (size_t)(row0 + ai * HALF + m * 16) * 3072 + ch) = w; }
	v_mul_f32_e32 v173, 0x3d372713, v125
	v_mul_f32_e32 v173, v125, v173
	v_fma_f32 v173, v125, v173, v125
	v_mul_f32_e32 v173, 0x3f4c422a, v173
	v_mul_f32_e32 v173, -2.0, v173
	v_mul_f32_e32 v173, 0x3fb8aa3b, v173
	v_mul_f32_e32 v175, 0x3d372713, v124
	v_exp_f32_e32 v173, v173
	v_mul_f32_e32 v175, v124, v175
	v_fma_f32 v175, v124, v175, v124
	v_mul_f32_e32 v175, 0x3f4c422a, v175
	v_mul_f32_e32 v175, -2.0, v175
	v_add_f32_e32 v173, 1.0, v173
	v_mul_f32_e32 v175, 0x3fb8aa3b, v175
	v_rcp_f32_e32 v173, v173
	v_exp_f32_e32 v175, v175
	v_mov_b32_e32 v228, v97
	v_mov_b32_e32 v229, v125
	v_pk_mul_f32 v[228:229], v[228:229], v[172:173]
	v_add_f32_e32 v173, 1.0, v175
	v_mul_f32_e32 v175, 0x3d372713, v123
	v_mul_f32_e32 v175, v123, v175
	v_fma_f32 v175, v123, v175, v123
	v_mul_f32_e32 v175, 0x3f4c422a, v175
	v_mul_f32_e32 v175, -2.0, v175
	v_mul_f32_e32 v175, 0x3fb8aa3b, v175
	v_rcp_f32_e32 v173, v173
	v_exp_f32_e32 v175, v175
	v_mul_f32_e32 v191, v228, v229
	v_mov_b32_e32 v228, v96
	v_mov_b32_e32 v229, v124
	v_pk_mul_f32 v[228:229], v[228:229], v[172:173]
	v_add_f32_e32 v173, 1.0, v175
	v_mul_f32_e32 v175, 0x3d372713, v122
	v_mul_f32_e32 v175, v122, v175
	v_fma_f32 v175, v122, v175, v122
	v_mul_f32_e32 v175, 0x3f4c422a, v175
	v_mul_f32_e32 v175, -2.0, v175
	v_mul_f32_e32 v175, 0x3fb8aa3b, v175
	v_rcp_f32_e32 v173, v173
	v_exp_f32_e32 v175, v175
	v_mul_f32_e32 v230, v228, v229
	v_mov_b32_e32 v228, v95
	v_mov_b32_e32 v229, v123
	v_pk_mul_f32 v[228:229], v[228:229], v[172:173]
	v_add_f32_e32 v173, 1.0, v175
	v_rcp_f32_e32 v173, v173
	v_mul_f32_e32 v175, v228, v229
	v_mov_b32_e32 v228, v94
	v_mov_b32_e32 v229, v122
	v_pk_mul_f32 v[228:229], v[228:229], v[172:173]
	s_nop 0
	v_mul_f32_e32 v173, v228, v229
	v_cvt_pk_bf16_f32 v228, v173, v175
	v_cvt_pk_bf16_f32 v229, v230, v191
	v_mov_b64_e32 v[230:231], s[26:27]
	v_mad_i64_i32 v[230:231], s[76:77], v181, s67, v[230:231]
	v_lshl_add_u64 v[230:231], v[162:163], 1, v[230:231]
	global_store_dwordx2 v[230:231], v[228:229], off

; __device__ __forceinline__ unsigned cvt_pk_bf16(float lo, float hi) { unsigned r; asm volatile("v_cvt_pk_bf16_f32 %0, %1, %2" : "=v"(r) : "v"(lo), "v"(hi)); return r; }
; __device__ __forceinline__ float gelu_tanh_f(float x) { const float u = 0.7978845608028654f * (x + 0.044715f * x * x * x); return x * fast_rcp(1.0f + __expf(-2.0f * u)); }
;     __device__ __forceinline__ void operator()(const f32x4 (&acc)[2][2][4][2], const Unit& u, int wr, int wc, int fr, int fq) const {
;     ...
;                 const int ch = ch0 + 4 * n;
;                 const f32x4 w0 = *(const f32x4*)(cw + ch), w1 = *(const f32x4*)(cw + 3072 + ch), w2 = *(const f32x4*)(cw + 6144 + ch), bb = *(const f32x4*)(cb + ch);
;                 float o[4][4], pp[4][4], gg[4][4];
; #pragma unroll
;                 for (int e = 0; e < 4; ++e) {
;                     float g[4], R[4], L[4];
; #pragma unroll
;                     for (int m = 0; m < 4; ++m) { g[m] = acc[ai][0][m][n][e] * rs[m];
;                         R[m] = __builtin_bit_cast(float, __builtin_amdgcn_mov_dpp(__builtin_bit_cast(int, g[m]), 0x121, 0xf, 0xf, true)); L[m] = __builtin_bit_cast(float, __builtin_amdgcn_mov_dpp(__builtin_bit_cast(int, g[m]), 0x12F, 0xf, 0xf, true)); }
; #pragma unroll
;                     for (int m = 0; m < 4; ++m) {
;                         const float gp = (fr == 0) ? (m > 0 ? R[m > 0 ? m - 1 : 0] : 0.f) : R[m];
;                         const float gn = (fr == 15) ? (m < 3 ? L[m < 3 ? m + 1 : 3] : 0.f) : L[m];
;                         const float pre = bb[e] + w0[e] * gp + w1[e] * g[m] + w2[e] * gn;
;                         pp[m][e] = pre; gg[m][e] = g[m];
;                         o[m][e] = gelu_tanh_f(pre) * (acc[ai][1][m][n][e] * rs[m]);
;                     }
;                 }
; #pragma unroll
;                 for (int m = 0; m < 4; ++m) {
;                     const bool edge = (m == 0 && fr == 0) || (m == 3 && fr == 15);
;                     if (!edge) { u32x2 w; w.x = cvt_pk_bf16(o[m][0], o[m][1]); w.y = cvt_pk_bf16(o[m][2], o[m][3]); *(u32x2*)(H + (size_t)(row0 + ai * HALF + m * 16) * 3072 + ch) = w; }
.LBB0_867:
	s_or_b64 exec, exec, s[76:77]
	v_or_b32_e32 v122, 4, v162
	v_ashrrev_i32_e32 v123, 31, v122
	v_lshlrev_b64 v[94:95], 2, v[122:123]
	v_mov_b32_e32 v118, v232
	v_mov_b32_e32 v119, v233
	v_mov_b32_e32 v120, v234
	v_mov_b32_e32 v121, v235
	v_mov_b32_e32 v106, v236
	v_mov_b32_e32 v107, v237
	v_mov_b32_e32 v108, v238
	v_mov_b32_e32 v109, v239
	v_lshl_add_u64 v[124:125], s[60:61], 0, v[94:95]
	v_mov_b32_e32 v110, v240
	v_mov_b32_e32 v111, v241
	v_mov_b32_e32 v112, v242
	v_mov_b32_e32 v113, v243
	v_lshl_add_u64 v[128:129], s[62:63], 0, v[94:95]
	v_mov_b32_e32 v114, v244
	v_mov_b32_e32 v115, v245
	v_mov_b32_e32 v116, v246
	v_mov_b32_e32 v117, v247
	v_pk_mul_f32 v[94:95], v[102:103], v[172:173]
	v_pk_mul_f32 v[96:97], v[104:105], v[172:173]
	v_mul_f32_e32 v201, v98, v183
	v_mov_b32_dpp v208, v94 row_ror:1 row_mask:0xf bank_mask:0xf bound_ctrl:1
	v_mov_b32_dpp v205, v95 row_ror:1 row_mask:0xf bank_mask:0xf bound_ctrl:1
	v_mov_b32_dpp v146, v96 row_ror:1 row_mask:0xf bank_mask:0xf bound_ctrl:1
	v_mov_b32_dpp v142, v97 row_ror:1 row_mask:0xf bank_mask:0xf bound_ctrl:1
	v_mul_f32_e32 v144, v90, v182
	v_mul_f32_e32 v186, v99, v183
	v_mul_f32_e32 v141, v91, v182
	v_mul_f32_e32 v140, v100, v183
	v_mul_f32_e32 v132, v101, v183
	v_cndmask_b32_e64 v91, v205, 0, s[4:5]
	v_cndmask_b32_e64 v90, v208, 0, s[4:5]
	v_cndmask_b32_e64 v211, v142, 0, s[4:5]
	v_cndmask_b32_e64 v210, v146, 0, s[4:5]
	v_mul_f32_e32 v99, v92, v182
	v_mul_f32_e32 v98, v93, v182
	v_mov_b32_dpp v207, v201 row_ror:15 row_mask:0xf bank_mask:0xf bound_ctrl:1
	v_mov_b32_dpp v92, v94 row_ror:15 row_mask:0xf bank_mask:0xf bound_ctrl:1
	v_mov_b32_dpp v93, v95 row_ror:15 row_mask:0xf bank_mask:0xf bound_ctrl:1
	v_mov_b32_dpp v206, v186 row_ror:15 row_mask:0xf bank_mask:0xf bound_ctrl:1
	v_mov_b32_dpp v145, v140 row_ror:15 row_mask:0xf bank_mask:0xf bound_ctrl:1
	v_mov_b32_dpp v191, v96 row_ror:15 row_mask:0xf bank_mask:0xf bound_ctrl:1
	v_mov_b32_dpp v209, v97 row_ror:15 row_mask:0xf bank_mask:0xf bound_ctrl:1
	v_mov_b32_dpp v143, v132 row_ror:15 row_mask:0xf bank_mask:0xf bound_ctrl:1
	v_pk_mul_f32 v[86:87], v[86:87], v[174:175]
	v_pk_mul_f32 v[88:89], v[88:89], v[174:175]
	v_cndmask_b32_e64 v93, v93, v206, s[8:9]
	v_cndmask_b32_e64 v92, v92, v207, s[8:9]
	v_cndmask_b32_e64 v213, v209, v143, s[8:9]
	v_cndmask_b32_e64 v212, v191, v145, s[8:9]
	v_mov_b32_dpp v204, v201 row_ror:1 row_mask:0xf bank_mask:0xf bound_ctrl:1
	v_mov_b32_dpp v200, v144 row_ror:1 row_mask:0xf bank_mask:0xf bound_ctrl:1
	v_mov_b32_dpp v203, v144 row_ror:15 row_mask:0xf bank_mask:0xf bound_ctrl:1
	v_mov_b32_dpp v185, v186 row_ror:1 row_mask:0xf bank_mask:0xf bound_ctrl:1
	v_mov_b32_dpp v147, v141 row_ror:1 row_mask:0xf bank_mask:0xf bound_ctrl:1
	v_mov_b32_dpp v187, v141 row_ror:15 row_mask:0xf bank_mask:0xf bound_ctrl:1
	v_mov_b32_dpp v202, v86 row_ror:1 row_mask:0xf bank_mask:0xf bound_ctrl:1
	v_mov_b32_dpp v148, v86 row_ror:15 row_mask:0xf bank_mask:0xf bound_ctrl:1
	v_mov_b32_dpp v184, v87 row_ror:1 row_mask:0xf bank_mask:0xf bound_ctrl:1
	v_mov_b32_dpp v149, v87 row_ror:15 row_mask:0xf bank_mask:0xf bound_ctrl:1
	v_mov_b32_dpp v139, v140 row_ror:1 row_mask:0xf bank_mask:0xf bound_ctrl:1
	v_mov_b32_dpp v105, v99 row_ror:1 row_mask:0xf bank_mask:0xf bound_ctrl:1
	v_mov_b32_dpp v133, v99 row_ror:15 row_mask:0xf bank_mask:0xf bound_ctrl:1
	v_mov_b32_dpp v102, v132 row_ror:1 row_mask:0xf bank_mask:0xf bound_ctrl:1
	v_mov_b32_dpp v103, v98 row_ror:1 row_mask:0xf bank_mask:0xf bound_ctrl:1
	v_mov_b32_dpp v104, v98 row_ror:15 row_mask:0xf bank_mask:0xf bound_ctrl:1
	v_mov_b32_dpp v130, v88 row_ror:1 row_mask:0xf bank_mask:0xf bound_ctrl:1
	v_mov_b32_dpp v101, v88 row_ror:15 row_mask:0xf bank_mask:0xf bound_ctrl:1
	v_mov_b32_dpp v131, v89 row_ror:1 row_mask:0xf bank_mask:0xf bound_ctrl:1
	v_mov_b32_dpp v100, v89 row_ror:15 row_mask:0xf bank_mask:0xf bound_ctrl:1
	s_nop 0
	v_pk_fma_f32 v[90:91], v[118:119], v[90:91], v[106:107]
	v_pk_fma_f32 v[210:211], v[120:121], v[210:211], v[108:109]
	s_nop 0
	v_pk_fma_f32 v[90:91], v[94:95], v[110:111], v[90:91]
	v_pk_fma_f32 v[210:211], v[96:97], v[112:113], v[210:211]
	s_nop 0
	v_pk_fma_f32 v[90:91], v[114:115], v[92:93], v[90:91]
	v_pk_fma_f32 v[92:93], v[116:117], v[212:213], v[210:211]
	s_and_saveexec_b64 s[74:75], s[6:7]
	s_cbranch_execz .LBB0_869
	v_mul_f32_e32 v191, 0x3d372713, v93
	v_mul_f32_e32 v191, v93, v191
	v_fma_f32 v191, v93, v191, v93
	v_mul_f32_e32 v191, 0x3f4c422a, v191
	v_mul_f32_e32 v191, -2.0, v191
	v_mul_f32_e32 v191, 0x3fb8aa3b, v191
	v_exp_f32_e32 v191, v191
	v_mul_f32_e32 v209, 0x3d372713, v92
	v_mov_b32_e32 v210, v69
	v_mov_b32_e32 v211, v93
	v_add_f32_e32 v191, 1.0, v191
	v_rcp_f32_e32 v213, v191
	v_mul_f32_e32 v191, v92, v209
	v_fma_f32 v191, v92, v191, v92
	v_mul_f32_e32 v191, 0x3f4c422a, v191
	v_mul_f32_e32 v191, -2.0, v191
	v_mul_f32_e32 v191, 0x3fb8aa3b, v191
	v_exp_f32_e32 v191, v191
	v_mov_b32_e32 v212, v172
	v_pk_mul_f32 v[210:211], v[210:211], v[212:213]
	v_mov_b32_e32 v212, v68
	v_add_f32_e32 v191, 1.0, v191
	v_mul_f32_e32 v209, v210, v211
	v_rcp_f32_e32 v211, v191
	v_mul_f32_e32 v191, 0x3d372713, v91
	v_mul_f32_e32 v191, v91, v191
	v_fma_f32 v191, v91, v191, v91
	v_mul_f32_e32 v191, 0x3f4c422a, v191
	v_mul_f32_e32 v191, -2.0, v191
	v_mul_f32_e32 v191, 0x3fb8aa3b, v191
	v_exp_f32_e32 v191, v191
	v_mov_b32_e32 v213, v92
	v_mov_b32_e32 v210, v172
	v_pk_mul_f32 v[210:211], v[212:213], v[210:211]
	v_add_f32_e32 v191, 1.0, v191
	v_mul_f32_e32 v214, v210, v211
	v_rcp_f32_e32 v211, v191
	v_mul_f32_e32 v191, 0x3d372713, v90
	v_mul_f32_e32 v191, v90, v191
	v_fma_f32 v191, v90, v191, v90
	v_mul_f32_e32 v191, 0x3f4c422a, v191
	v_mul_f32_e32 v191, -2.0, v191
	v_mul_f32_e32 v191, 0x3fb8aa3b, v191
	v_exp_f32_e32 v191, v191
	v_mov_b32_e32 v212, v67
	v_mov_b32_e32 v213, v91
	v_mov_b32_e32 v210, v172
	v_pk_mul_f32 v[210:211], v[212:213], v[210:211]
	v_add_f32_e32 v191, 1.0, v191
	v_mul_f32_e32 v215, v210, v211
	v_rcp_f32_e32 v211, v191
	v_mov_b32_e32 v212, v66
	v_mov_b32_e32 v213, v90
	v_mov_b32_e32 v210, v172
	v_pk_mul_f32 v[210:211], v[212:213], v[210:211]
	v_mov_b64_e32 v[212:213], s[26:27]
	v_mad_i64_i32 v[212:213], s[76:77], v181, s67, v[212:213]
	v_lshl_add_u64 v[212:213], v[162:163], 1, v[212:213]
	v_mul_f32_e32 v191, v210, v211
	v_cvt_pk_bf16_f32 v210, v191, v215
	v_cvt_pk_bf16_f32 v211, v214, v209
	global_store_dwordx2 v[212:213], v[210:211], off offset:8

; __device__ __forceinline__ unsigned cvt_pk_bf16(float lo, float hi) { unsigned r; asm volatile("v_cvt_pk_bf16_f32 %0, %1, %2" : "=v"(r) : "v"(lo), "v"(hi)); return r; }
; __device__ __forceinline__ float gelu_tanh_f(float x) { const float u = 0.7978845608028654f * (x + 0.044715f * x * x * x); return x * fast_rcp(1.0f + __expf(-2.0f * u)); }
;     __device__ __forceinline__ void operator()(const f32x4 (&acc)[2][2][4][2], const Unit& u, int wr, int wc, int fr, int fq) const {
;     ...
;                 const int ch = ch0 + 4 * n;
;                 const f32x4 w0 = *(const f32x4*)(cw + ch), w1 = *(const f32x4*)(cw + 3072 + ch), w2 = *(const f32x4*)(cw + 6144 + ch), bb = *(const f32x4*)(cb + ch);
;                 float o[4][4], pp[4][4], gg[4][4];
; #pragma unroll
;                 for (int e = 0; e < 4; ++e) {
;                     float g[4], R[4], L[4];
; #pragma unroll
;                     for (int m = 0; m < 4; ++m) { g[m] = acc[ai][0][m][n][e] * rs[m];
;                         R[m] = __builtin_bit_cast(float, __builtin_amdgcn_mov_dpp(__builtin_bit_cast(int, g[m]), 0x121, 0xf, 0xf, true)); L[m] = __builtin_bit_cast(float, __builtin_amdgcn_mov_dpp(__builtin_bit_cast(int, g[m]), 0x12F, 0xf, 0xf, true)); }
; #pragma unroll
;                     for (int m = 0; m < 4; ++m) {
;                         const float gp = (fr == 0) ? (m > 0 ? R[m > 0 ? m - 1 : 0] : 0.f) : R[m];
;                         const float gn = (fr == 15) ? (m < 3 ? L[m < 3 ? m + 1 : 3] : 0.f) : L[m];
;                         const float pre = bb[e] + w0[e] * gp + w1[e] * g[m] + w2[e] * gn;
;                         pp[m][e] = pre; gg[m][e] = g[m];
;                         o[m][e] = gelu_tanh_f(pre) * (acc[ai][1][m][n][e] * rs[m]);
;                     }
;                 }
; #pragma unroll
;                 for (int m = 0; m < 4; ++m) {
;                     const bool edge = (m == 0 && fr == 0) || (m == 3 && fr == 15);
;                     if (!edge) { u32x2 w; w.x = cvt_pk_bf16(o[m][0], o[m][1]); w.y = cvt_pk_bf16(o[m][2], o[m][3]); *(u32x2*)(H + (size_t)(row0 + ai * HALF + m * 16) * 3072 + ch) = w; }
.LBB0_883:
	s_or_b64 exec, exec, s[76:77]
	v_mov_b32_e32 v46, v232
	v_mov_b32_e32 v47, v233
	v_mov_b32_e32 v48, v234
	v_mov_b32_e32 v49, v235
	v_mov_b32_e32 v34, v236
	v_mov_b32_e32 v35, v237
	v_mov_b32_e32 v36, v238
	v_mov_b32_e32 v37, v239
	v_mov_b32_e32 v38, v240
	v_mov_b32_e32 v39, v241
	v_mov_b32_e32 v40, v242
	v_mov_b32_e32 v41, v243
	v_mov_b32_e32 v42, v244
	v_mov_b32_e32 v43, v245
	v_mov_b32_e32 v44, v246
	v_mov_b32_e32 v45, v247
	v_pk_mul_f32 v[30:31], v[30:31], v[86:87]
	v_pk_mul_f32 v[32:33], v[32:33], v[86:87]
	v_mul_f32_e32 v79, v26, v91
	v_mov_b32_dpp v97, v30 row_ror:1 row_mask:0xf bank_mask:0xf bound_ctrl:1
	v_mov_b32_dpp v94, v31 row_ror:1 row_mask:0xf bank_mask:0xf bound_ctrl:1
	v_mov_b32_dpp v70, v32 row_ror:1 row_mask:0xf bank_mask:0xf bound_ctrl:1
	v_mov_b32_dpp v65, v33 row_ror:1 row_mask:0xf bank_mask:0xf bound_ctrl:1
	v_mul_f32_e32 v68, v22, v90
	v_mul_f32_e32 v76, v27, v91
	v_mul_f32_e32 v64, v23, v90
	v_mul_f32_e32 v63, v28, v91
	v_mul_f32_e32 v56, v29, v91
	v_cndmask_b32_e64 v23, v94, 0, s[4:5]
	v_cndmask_b32_e64 v22, v97, 0, s[4:5]
	v_cndmask_b32_e64 v99, v65, 0, s[4:5]
	v_cndmask_b32_e64 v98, v70, 0, s[4:5]
	v_mul_f32_e32 v27, v24, v90
	v_mul_f32_e32 v26, v25, v90
	v_mov_b32_dpp v96, v79 row_ror:15 row_mask:0xf bank_mask:0xf bound_ctrl:1
	v_mov_b32_dpp v24, v30 row_ror:15 row_mask:0xf bank_mask:0xf bound_ctrl:1
	v_mov_b32_dpp v25, v31 row_ror:15 row_mask:0xf bank_mask:0xf bound_ctrl:1
	v_mov_b32_dpp v95, v76 row_ror:15 row_mask:0xf bank_mask:0xf bound_ctrl:1
	v_mov_b32_dpp v69, v63 row_ror:15 row_mask:0xf bank_mask:0xf bound_ctrl:1
	v_mov_b32_dpp v100, v32 row_ror:15 row_mask:0xf bank_mask:0xf bound_ctrl:1
	v_mov_b32_dpp v101, v33 row_ror:15 row_mask:0xf bank_mask:0xf bound_ctrl:1
	v_mov_b32_dpp v67, v56 row_ror:15 row_mask:0xf bank_mask:0xf bound_ctrl:1
	v_pk_mul_f32 v[18:19], v[18:19], v[88:89]
	v_pk_mul_f32 v[20:21], v[20:21], v[88:89]
	v_cndmask_b32_e64 v25, v25, v95, s[8:9]
	v_cndmask_b32_e64 v24, v24, v96, s[8:9]
	v_cndmask_b32_e64 v101, v101, v67, s[8:9]
	v_cndmask_b32_e64 v100, v100, v69, s[8:9]
	v_mov_b32_dpp v93, v79 row_ror:1 row_mask:0xf bank_mask:0xf bound_ctrl:1
	v_mov_b32_dpp v78, v68 row_ror:1 row_mask:0xf bank_mask:0xf bound_ctrl:1
	v_mov_b32_dpp v81, v68 row_ror:15 row_mask:0xf bank_mask:0xf bound_ctrl:1
	v_mov_b32_dpp v75, v76 row_ror:1 row_mask:0xf bank_mask:0xf bound_ctrl:1
	v_mov_b32_dpp v71, v64 row_ror:1 row_mask:0xf bank_mask:0xf bound_ctrl:1
	v_mov_b32_dpp v77, v64 row_ror:15 row_mask:0xf bank_mask:0xf bound_ctrl:1
	v_mov_b32_dpp v80, v18 row_ror:1 row_mask:0xf bank_mask:0xf bound_ctrl:1
	v_mov_b32_dpp v72, v18 row_ror:15 row_mask:0xf bank_mask:0xf bound_ctrl:1
	v_mov_b32_dpp v74, v19 row_ror:1 row_mask:0xf bank_mask:0xf bound_ctrl:1
	v_mov_b32_dpp v73, v19 row_ror:15 row_mask:0xf bank_mask:0xf bound_ctrl:1
	v_mov_b32_dpp v62, v63 row_ror:1 row_mask:0xf bank_mask:0xf bound_ctrl:1
	v_mov_b32_dpp v53, v27 row_ror:1 row_mask:0xf bank_mask:0xf bound_ctrl:1
	v_mov_b32_dpp v57, v27 row_ror:15 row_mask:0xf bank_mask:0xf bound_ctrl:1
	v_mov_b32_dpp v50, v56 row_ror:1 row_mask:0xf bank_mask:0xf bound_ctrl:1
	v_mov_b32_dpp v51, v26 row_ror:1 row_mask:0xf bank_mask:0xf bound_ctrl:1
	v_mov_b32_dpp v52, v26 row_ror:15 row_mask:0xf bank_mask:0xf bound_ctrl:1
	v_mov_b32_dpp v54, v20 row_ror:1 row_mask:0xf bank_mask:0xf bound_ctrl:1
	v_mov_b32_dpp v29, v20 row_ror:15 row_mask:0xf bank_mask:0xf bound_ctrl:1
	v_mov_b32_dpp v55, v21 row_ror:1 row_mask:0xf bank_mask:0xf bound_ctrl:1
	v_mov_b32_dpp v28, v21 row_ror:15 row_mask:0xf bank_mask:0xf bound_ctrl:1
	s_nop 0
	v_pk_fma_f32 v[22:23], v[46:47], v[22:23], v[34:35]
	v_pk_fma_f32 v[98:99], v[48:49], v[98:99], v[36:37]
	s_nop 0
	v_pk_fma_f32 v[22:23], v[30:31], v[38:39], v[22:23]
	v_pk_fma_f32 v[98:99], v[32:33], v[40:41], v[98:99]
	s_nop 0
	v_pk_fma_f32 v[22:23], v[42:43], v[24:25], v[22:23]
	v_pk_fma_f32 v[24:25], v[44:45], v[100:101], v[98:99]
	s_and_saveexec_b64 s[74:75], s[6:7]
	s_cbranch_execz .LBB0_885
	v_mul_f32_e32 v98, 0x3d372713, v25
	v_mul_f32_e32 v98, v25, v98
	v_fma_f32 v98, v25, v98, v25
	v_mul_f32_e32 v98, 0x3f4c422a, v98
	v_mul_f32_e32 v98, -2.0, v98
	v_mul_f32_e32 v98, 0x3fb8aa3b, v98
	v_exp_f32_e32 v100, v98
	v_mul_f32_e32 v102, 0x3d372713, v24
	v_mov_b32_e32 v98, v5
	v_mov_b32_e32 v99, v25
	v_add_f32_e32 v100, 1.0, v100
	v_rcp_f32_e32 v101, v100
	v_mul_f32_e32 v100, v24, v102
	v_fma_f32 v100, v24, v100, v24
	v_mul_f32_e32 v100, 0x3f4c422a, v100
	v_mul_f32_e32 v100, -2.0, v100
	v_mul_f32_e32 v100, 0x3fb8aa3b, v100
	v_exp_f32_e32 v102, v100
	v_mov_b32_e32 v100, v86
	v_pk_mul_f32 v[98:99], v[98:99], v[100:101]
	v_mov_b32_e32 v100, v4
	v_mul_f32_e32 v103, v98, v99
	v_add_f32_e32 v98, 1.0, v102
	v_rcp_f32_e32 v99, v98
	v_mul_f32_e32 v98, 0x3d372713, v23
	v_mul_f32_e32 v98, v23, v98
	v_fma_f32 v98, v23, v98, v23
	v_mul_f32_e32 v98, 0x3f4c422a, v98
	v_mul_f32_e32 v98, -2.0, v98
	v_mul_f32_e32 v98, 0x3fb8aa3b, v98
	v_exp_f32_e32 v102, v98
	v_mov_b32_e32 v101, v24
	v_mov_b32_e32 v98, v86
	v_pk_mul_f32 v[98:99], v[100:101], v[98:99]
	v_mov_b32_e32 v100, v3
	v_mul_f32_e32 v104, v98, v99
	v_add_f32_e32 v98, 1.0, v102
	v_rcp_f32_e32 v99, v98
	v_mul_f32_e32 v98, 0x3d372713, v22
	v_mul_f32_e32 v98, v22, v98
	v_fma_f32 v98, v22, v98, v22
	v_mul_f32_e32 v98, 0x3f4c422a, v98
	v_mul_f32_e32 v98, -2.0, v98
	v_mul_f32_e32 v98, 0x3fb8aa3b, v98
	v_exp_f32_e32 v102, v98
	v_mov_b32_e32 v101, v23
	v_mov_b32_e32 v98, v86
	v_pk_mul_f32 v[98:99], v[100:101], v[98:99]
	v_mov_b32_e32 v100, v2
	v_mul_f32_e32 v105, v98, v99
	v_add_f32_e32 v98, 1.0, v102
	v_rcp_f32_e32 v99, v98
	v_mov_b32_e32 v101, v22
	v_mov_b32_e32 v98, v86
	v_pk_mul_f32 v[98:99], v[100:101], v[98:99]
	v_mov_b64_e32 v[100:101], s[26:27]
	v_mad_i64_i32 v[100:101], s[76:77], v92, s67, v[100:101]
	v_mul_f32_e32 v98, v98, v99
	v_lshl_add_u64 v[100:101], v[162:163], 1, v[100:101]
	v_cvt_pk_bf16_f32 v98, v98, v105
	v_cvt_pk_bf16_f32 v99, v104, v103
	global_store_dwordx2 v[100:101], v[98:99], off offset:8
